# hg_prep prefetch: top-of-unit wait counts exactly the stores issued behind the prefetch per wave class (does not wait for the previous unit's stores)
# baseline (speedup 1.0000x reference)
; #define GAS __attribute__((address_space(1)))
; #define VM_WAIT() asm volatile("s_waitcnt vmcnt(0)" ::: "memory")
; __device__ __forceinline__ void hg_prep(const Frame& F, unsigned char* ws, unsigned char* sfr) {
;     ...
;     for (int u = F.vcu; u < 2048 + NSEQ_S; u += F.G) {
;         int t0, nvalid, h; unsigned char *qf, *vf, *lf; int qp, lp;
;         if (u < 2048) { const int b = u >> 8, n = u & 63; h = (u >> 6) & 3; t0 = b * 2048 + n * 32; nvalid = 32;
;             const size_t e0 = (size_t)t0 * DA + h * 128; qf = ws + WS_Q + e0 * 2; vf = ws + WS_V + e0 * 2; lf = ws + WS_LOGF + e0 * 4; qp = 1024; lp = 2048; }
;         else { const int su = u - 2048, b = su >> 2; h = su & 3; t0 = TP + b * 8; nvalid = 8;
;             unsigned char* base = sfr + (size_t)su * 65536; qf = base; vf = base + 8192; lf = base + 16384; qp = 256; lp = 512; }
;         f32x4 lf0 = {0.f, 0.f, 0.f, 0.f}, lf1 = {0.f, 0.f, 0.f, 0.f}; v4u q8 = {0u, 0u, 0u, 0u}, v8 = {0u, 0u, 0u, 0u};
;         if (c < nvalid) { const size_t e = (size_t)(t0 + c) * DA + h * 128 + 8 * kg;
;             lf0 = NTL((const GAS f32x4*)(LFg + e)); lf1 = NTL((const GAS f32x4*)(LFg + e + 4)); q8 = NTL((const GAS v4u*)(Qg + e)); v8 = NTL((const GAS v4u*)(Vg + e)); }
;         VM_WAIT();
.LBB0_439:
	s_cmp_eq_u32 s63, s33
	s_cbranch_scc1 .Lhg_w0
	v_readfirstlane_b32 s98, v0
	s_lshr_b32 s98, s98, 6
	s_cmp_gt_u32 s98, 3
	s_cbranch_scc1 .Lhg_w6
	s_cmp_gt_u32 s98, 1
	s_cbranch_scc1 .Lhg_w2
	s_cmp_eq_u32 s98, 1
	s_cbranch_scc1 .Lhg_w3
	s_waitcnt vmcnt(5)
	s_branch .Lhg_wd
.Lhg_w3:
	s_waitcnt vmcnt(3)
	s_branch .Lhg_wd
.Lhg_w2:
	s_waitcnt vmcnt(2)
	s_branch .Lhg_wd
.Lhg_w6:
	s_waitcnt vmcnt(6)
	s_branch .Lhg_wd

; #define GAS __attribute__((address_space(1)))
; __device__ __forceinline__ void hg_prep(const Frame& F, unsigned char* ws, unsigned char* sfr) {
;     ...
;     for (int u = F.vcu; u < 2048 + NSEQ_S; u += F.G) {
;         int t0, nvalid, h; unsigned char *qf, *vf, *lf; int qp, lp;
;         if (u < 2048) { const int b = u >> 8, n = u & 63; h = (u >> 6) & 3; t0 = b * 2048 + n * 32; nvalid = 32;
;             const size_t e0 = (size_t)t0 * DA + h * 128; qf = ws + WS_Q + e0 * 2; vf = ws + WS_V + e0 * 2; lf = ws + WS_LOGF + e0 * 4; qp = 1024; lp = 2048; }
;         else { const int su = u - 2048, b = su >> 2; h = su & 3; t0 = TP + b * 8; nvalid = 8;
;             unsigned char* base = sfr + (size_t)su * 65536; qf = base; vf = base + 8192; lf = base + 16384; qp = 256; lp = 512; }
;         f32x4 lf0 = {0.f, 0.f, 0.f, 0.f}, lf1 = {0.f, 0.f, 0.f, 0.f}; v4u q8 = {0u, 0u, 0u, 0u}, v8 = {0u, 0u, 0u, 0u};
;         if (c < nvalid) { const size_t e = (size_t)(t0 + c) * DA + h * 128 + 8 * kg;
;             lf0 = NTL((const GAS f32x4*)(LFg + e)); lf1 = NTL((const GAS f32x4*)(LFg + e + 4)); q8 = NTL((const GAS v4u*)(Qg + e)); v8 = NTL((const GAS v4u*)(Vg + e)); }
.Lhg_wd:
	v_mov_b32_e32 v18, v200
	v_mov_b32_e32 v19, v201
	v_mov_b32_e32 v20, v202
	v_mov_b32_e32 v21, v203
	v_mov_b32_e32 v2, v204
	v_mov_b32_e32 v3, v205
	v_mov_b32_e32 v4, v206
	v_mov_b32_e32 v5, v207
	v_mov_b32_e32 v6, v208
	v_mov_b32_e32 v7, v209
	v_mov_b32_e32 v8, v210
	v_mov_b32_e32 v9, v211
	v_mov_b32_e32 v10, v212
	v_mov_b32_e32 v11, v213
	v_mov_b32_e32 v12, v214
	v_mov_b32_e32 v13, v215
	s_add_i32 s98, s63, s18
	s_cmpk_lt_i32 s98, 0xa00
	s_cbranch_scc0 .Lhgpf_none
	s_cmpk_gt_i32 s98, 0x7ff
	s_cbranch_scc1 .Lhgpf_smp_b
	s_lshl_b32 s99, s98, 3
	s_and_b32 s99, s99, 0xfffff800
	s_lshl_b32 s100, s98, 5
	s_and_b32 s100, s100, 0x7e0
	s_or_b32 s99, s99, s100
	s_bfe_u32 s100, s98, 0x20006
	s_movk_i32 s101, 32
	s_branch .Lhgpf_go_b
